# first grid barrier: per-XCD workgroup count / XCD count computed by thread 0 early (while the ada weight loads are in flight) instead of inside the barrier
# baseline (speedup 1.0000x reference)
.LBB0_30:
	v_readlane_b32 s3, v255, 5
	v_readlane_b32 s0, v255, 0
	v_readlane_b32 s1, v255, 1
	s_sub_u32 s0, s0, 0xc8
	s_subb_u32 s1, s1, 0
	s_load_dwordx2 s[74:75], s[0:1], 0x38
	v_lshrrev_b32_e32 v82, 4, v170
	s_lshl_b32 s73, s3, 7
	v_lshl_add_u32 v80, v82, 3, s73
	v_lshlrev_b32_e32 v83, 4, v170
	s_mul_i32 s73, s3, 0x3000
	v_add_u32_e32 v128, s73, v83
	v_mov_b32_e32 v129, v83
	v_add_u32_e32 v130, 0xc000, v83
	v_and_b32_e32 v134, 15, v170
	v_mul_u32_u24_e32 v134, 12, v134
	v_mov_b32_e32 v4, 0
	v_mov_b32_e32 v16, 0
	v_mov_b32_e32 v5, 0
	v_mov_b32_e32 v17, 0
	v_mov_b32_e32 v6, 0
	v_mov_b32_e32 v18, 0
	v_mov_b32_e32 v7, 0
	v_mov_b32_e32 v19, 0
	v_mov_b32_e32 v8, 0
	v_mov_b32_e32 v20, 0
	v_mov_b32_e32 v9, 0
	v_mov_b32_e32 v21, 0
	v_mov_b32_e32 v10, 0
	v_mov_b32_e32 v22, 0
	v_mov_b32_e32 v11, 0
	v_mov_b32_e32 v23, 0
	v_mov_b32_e32 v12, 0
	v_mov_b32_e32 v24, 0
	v_mov_b32_e32 v13, 0
	v_mov_b32_e32 v25, 0
	v_mov_b32_e32 v14, 0
	v_mov_b32_e32 v26, 0
	v_mov_b32_e32 v15, 0
	v_mov_b32_e32 v27, 0
	s_waitcnt lgkmcnt(0)
	s_mul_i32 s73, s95, 0xc0
	v_add_u32_e32 v82, s73, v134
	global_load_dwordx3 v[236:238], v82, s[74:75]
	s_waitcnt vmcnt(0)
	v_add_u32_e32 v82, 0, v80
	v_mad_u64_u32 v[2:3], s[0:1], v82, s69, v[226:227]
	global_load_dwordx3 v[28:30], v[2:3], off nt
	v_add_u32_e32 v82, 1, v80
	v_mad_u64_u32 v[2:3], s[0:1], v82, s69, v[226:227]
	global_load_dwordx3 v[32:34], v[2:3], off nt
	v_add_u32_e32 v82, 2, v80
	v_mad_u64_u32 v[2:3], s[0:1], v82, s69, v[226:227]
	global_load_dwordx3 v[36:38], v[2:3], off nt
	v_add_u32_e32 v82, 3, v80
	v_mad_u64_u32 v[2:3], s[0:1], v82, s69, v[226:227]
	global_load_dwordx3 v[40:42], v[2:3], off nt
	v_add_u32_e32 v82, 4, v80
	v_mad_u64_u32 v[2:3], s[0:1], v82, s69, v[226:227]
	global_load_dwordx3 v[44:46], v[2:3], off nt
	v_add_u32_e32 v82, 5, v80
	v_mad_u64_u32 v[2:3], s[0:1], v82, s69, v[226:227]
	global_load_dwordx3 v[48:50], v[2:3], off nt
	v_add_u32_e32 v82, 6, v80
	v_mad_u64_u32 v[2:3], s[0:1], v82, s69, v[226:227]
	global_load_dwordx3 v[52:54], v[2:3], off nt
	v_add_u32_e32 v82, 7, v80
	v_mad_u64_u32 v[2:3], s[0:1], v82, s69, v[226:227]
	global_load_dwordx3 v[56:58], v[2:3], off nt
	v_add_u32_e32 v82, 32, v80
	v_mad_u64_u32 v[2:3], s[0:1], v82, s69, v[226:227]
	global_load_dwordx3 v[60:62], v[2:3], off nt
	v_add_u32_e32 v82, 33, v80
	v_mad_u64_u32 v[2:3], s[0:1], v82, s69, v[226:227]
	global_load_dwordx3 v[64:66], v[2:3], off nt
	v_add_u32_e32 v82, 34, v80
	v_mad_u64_u32 v[2:3], s[0:1], v82, s69, v[226:227]
	global_load_dwordx3 v[68:70], v[2:3], off nt
	v_add_u32_e32 v82, 35, v80
	v_mad_u64_u32 v[2:3], s[0:1], v82, s69, v[226:227]
	global_load_dwordx3 v[72:74], v[2:3], off nt
	v_add_u32_e32 v82, 36, v80
	v_mad_u64_u32 v[2:3], s[0:1], v82, s69, v[226:227]
	global_load_dwordx3 v[76:78], v[2:3], off nt
	v_add_u32_e32 v82, 37, v80
	v_mad_u64_u32 v[2:3], s[0:1], v82, s69, v[226:227]
	global_load_dwordx3 v[84:86], v[2:3], off nt
	v_add_u32_e32 v82, 38, v80
	v_mad_u64_u32 v[2:3], s[0:1], v82, s69, v[226:227]
	global_load_dwordx3 v[88:90], v[2:3], off nt
	v_add_u32_e32 v82, 39, v80
	v_mad_u64_u32 v[2:3], s[0:1], v82, s69, v[226:227]
	global_load_dwordx3 v[92:94], v[2:3], off nt
	v_add_u32_e32 v82, 64, v80
	v_mad_u64_u32 v[2:3], s[0:1], v82, s69, v[226:227]
	global_load_dwordx3 v[96:98], v[2:3], off nt
	v_add_u32_e32 v82, 65, v80
	v_mad_u64_u32 v[2:3], s[0:1], v82, s69, v[226:227]
	global_load_dwordx3 v[100:102], v[2:3], off nt
	v_add_u32_e32 v82, 66, v80
	v_mad_u64_u32 v[2:3], s[0:1], v82, s69, v[226:227]
	global_load_dwordx3 v[104:106], v[2:3], off nt
	v_add_u32_e32 v82, 67, v80
	v_mad_u64_u32 v[2:3], s[0:1], v82, s69, v[226:227]
	global_load_dwordx3 v[108:110], v[2:3], off nt
	v_add_u32_e32 v82, 68, v80
	v_mad_u64_u32 v[2:3], s[0:1], v82, s69, v[226:227]
	global_load_dwordx3 v[112:114], v[2:3], off nt
	v_add_u32_e32 v82, 69, v80
	v_mad_u64_u32 v[2:3], s[0:1], v82, s69, v[226:227]
	global_load_dwordx3 v[116:118], v[2:3], off nt
	v_add_u32_e32 v82, 70, v80
	v_mad_u64_u32 v[2:3], s[0:1], v82, s69, v[226:227]
	global_load_dwordx3 v[120:122], v[2:3], off nt
	v_add_u32_e32 v82, 71, v80
	v_mad_u64_u32 v[2:3], s[0:1], v82, s69, v[226:227]
	global_load_dwordx3 v[124:126], v[2:3], off nt
	v_add_u32_e32 v82, 96, v80
	v_mad_u64_u32 v[2:3], s[0:1], v82, s69, v[226:227]
	global_load_dwordx3 v[140:142], v[2:3], off nt
	v_add_u32_e32 v82, 97, v80
	v_mad_u64_u32 v[2:3], s[0:1], v82, s69, v[226:227]
	global_load_dwordx3 v[144:146], v[2:3], off nt
	v_add_u32_e32 v82, 98, v80
	v_mad_u64_u32 v[2:3], s[0:1], v82, s69, v[226:227]
	global_load_dwordx3 v[148:150], v[2:3], off nt
	v_add_u32_e32 v82, 99, v80
	v_mad_u64_u32 v[2:3], s[0:1], v82, s69, v[226:227]
	global_load_dwordx3 v[152:154], v[2:3], off nt
	v_add_u32_e32 v82, 100, v80
	v_mad_u64_u32 v[2:3], s[0:1], v82, s69, v[226:227]
	global_load_dwordx3 v[160:162], v[2:3], off nt
	v_add_u32_e32 v82, 101, v80
	v_mad_u64_u32 v[2:3], s[0:1], v82, s69, v[226:227]
	global_load_dwordx3 v[164:166], v[2:3], off nt
	v_add_u32_e32 v82, 102, v80
	v_mad_u64_u32 v[2:3], s[0:1], v82, s69, v[226:227]
	global_load_dwordx3 v[172:174], v[2:3], off nt
	v_add_u32_e32 v82, 103, v80
	v_mad_u64_u32 v[2:3], s[0:1], v82, s69, v[226:227]
	global_load_dwordx3 v[176:178], v[2:3], off nt
	s_cmp_lg_u32 s3, 0
	s_cbranch_scc1 .Lnx_odd_skip
	s_mov_b64 exec, 1
	v_mov_b32_e32 v196, 0x400
	s_mov_b32 s73, 0
.Lnx_odd_poll:
	global_load_dword v180, v196, s[70:71] offset:0 sc1
	global_load_dword v181, v196, s[70:71] offset:256 sc1
	global_load_dword v182, v196, s[70:71] offset:512 sc1
	global_load_dword v183, v196, s[70:71] offset:768 sc1
	global_load_dword v184, v196, s[70:71] offset:1024 sc1
	global_load_dword v185, v196, s[70:71] offset:1280 sc1
	global_load_dword v186, v196, s[70:71] offset:1536 sc1
	global_load_dword v187, v196, s[70:71] offset:1792 sc1
	global_load_dword v188, v196, s[70:71] offset:2048 sc1
	global_load_dword v189, v196, s[70:71] offset:2304 sc1
	global_load_dword v190, v196, s[70:71] offset:2560 sc1
	global_load_dword v191, v196, s[70:71] offset:2816 sc1
	global_load_dword v192, v196, s[70:71] offset:3072 sc1
	global_load_dword v193, v196, s[70:71] offset:3328 sc1
	global_load_dword v194, v196, s[70:71] offset:3584 sc1
	global_load_dword v195, v196, s[70:71] offset:3840 sc1
	s_add_i32 s73, s73, 1
	s_waitcnt vmcnt(0)
	v_add3_u32 v197, v180, v181, v182
	v_add3_u32 v197, v197, v183, v184
	v_add3_u32 v197, v197, v185, v186
	v_add3_u32 v197, v197, v187, v188
	v_add3_u32 v197, v197, v189, v190
	v_add3_u32 v197, v197, v191, v192
	v_add3_u32 v197, v197, v193, v194
	v_add_u32_e32 v197, v197, v195
	v_cmp_eq_u32_e32 vcc, s96, v197
	s_cbranch_vccnz .Lnx_odd_done
	s_sleep 1
	s_cmp_lt_u32 s73, 0x8000
	s_cbranch_scc1 .Lnx_odd_poll
.Lnx_odd_done:
	v_readlane_b32 s73, v255, 2
	s_and_b32 s73, s73, 15
	s_lshl_b32 s73, s73, 8
	s_add_i32 s73, s73, 0x400
	v_mov_b32_e32 v198, s73
	global_load_dword v198, v198, s[70:71] sc1
	v_min_u32_e32 v180, 1, v180
	v_min_u32_e32 v181, 1, v181
	v_min_u32_e32 v182, 1, v182
	v_min_u32_e32 v183, 1, v183
	v_min_u32_e32 v184, 1, v184
	v_min_u32_e32 v185, 1, v185
	v_min_u32_e32 v186, 1, v186
	v_min_u32_e32 v187, 1, v187
	v_min_u32_e32 v188, 1, v188
	v_min_u32_e32 v189, 1, v189
	v_min_u32_e32 v190, 1, v190
	v_min_u32_e32 v191, 1, v191
	v_min_u32_e32 v192, 1, v192
	v_min_u32_e32 v193, 1, v193
	v_min_u32_e32 v194, 1, v194
	v_min_u32_e32 v195, 1, v195
	v_add3_u32 v199, v180, v181, v182
	v_add3_u32 v199, v199, v183, v184
	v_add3_u32 v199, v199, v185, v186
	v_add3_u32 v199, v199, v187, v188
	v_add3_u32 v199, v199, v189, v190
	v_add3_u32 v199, v199, v191, v192
	v_add3_u32 v199, v199, v193, v194
	v_add_u32_e32 v199, v199, v195
	v_max_u32_e32 v199, 1, v199
	v_mov_b32_e32 v196, 0x20000
	s_waitcnt vmcnt(0)
	v_max_u32_e32 v198, 1, v198
	ds_write_b32 v196, v198
	ds_write_b32 v196, v199 offset:4
	s_waitcnt lgkmcnt(0)
	s_mov_b64 exec, -1
.Lnx_odd_skip:
	s_waitcnt vmcnt(24)
	v_cvt_pk_bf16_f32 v180, v28, v32
	v_cvt_pk_bf16_f32 v181, v36, v40
	v_cvt_pk_bf16_f32 v182, v44, v48
	v_cvt_pk_bf16_f32 v183, v52, v56
	v_cvt_pk_bf16_f32 v184, v29, v33
	v_cvt_pk_bf16_f32 v185, v37, v41
	v_cvt_pk_bf16_f32 v186, v45, v49
	v_cvt_pk_bf16_f32 v187, v53, v57
	v_cvt_pk_bf16_f32 v188, v30, v34
	v_cvt_pk_bf16_f32 v189, v38, v42
	v_cvt_pk_bf16_f32 v190, v46, v50
	v_cvt_pk_bf16_f32 v191, v54, v58
	ds_write_b128 v128, v[180:183] offset:0
	ds_write_b128 v128, v[184:187] offset:1024
	ds_write_b128 v128, v[188:191] offset:2048
	s_waitcnt vmcnt(16)
	v_cvt_pk_bf16_f32 v192, v60, v64
	v_cvt_pk_bf16_f32 v193, v68, v72
	v_cvt_pk_bf16_f32 v194, v76, v84
	v_cvt_pk_bf16_f32 v195, v88, v92
	v_cvt_pk_bf16_f32 v196, v61, v65
	v_cvt_pk_bf16_f32 v197, v69, v73
	v_cvt_pk_bf16_f32 v198, v77, v85
	v_cvt_pk_bf16_f32 v199, v89, v93
	v_cvt_pk_bf16_f32 v200, v62, v66
	v_cvt_pk_bf16_f32 v201, v70, v74
	v_cvt_pk_bf16_f32 v202, v78, v86
	v_cvt_pk_bf16_f32 v203, v90, v94
	ds_write_b128 v128, v[192:195] offset:3072
	ds_write_b128 v128, v[196:199] offset:4096
	ds_write_b128 v128, v[200:203] offset:5120
	s_waitcnt vmcnt(8)
	v_cvt_pk_bf16_f32 v204, v96, v100
	v_cvt_pk_bf16_f32 v205, v104, v108
	v_cvt_pk_bf16_f32 v206, v112, v116
	v_cvt_pk_bf16_f32 v207, v120, v124
	v_cvt_pk_bf16_f32 v208, v97, v101
	v_cvt_pk_bf16_f32 v209, v105, v109
	v_cvt_pk_bf16_f32 v210, v113, v117
	v_cvt_pk_bf16_f32 v211, v121, v125
	v_cvt_pk_bf16_f32 v212, v98, v102
	v_cvt_pk_bf16_f32 v213, v106, v110
	v_cvt_pk_bf16_f32 v214, v114, v118
	v_cvt_pk_bf16_f32 v215, v122, v126
	ds_write_b128 v128, v[204:207] offset:6144
	ds_write_b128 v128, v[208:211] offset:7168
	ds_write_b128 v128, v[212:215] offset:8192
	s_waitcnt vmcnt(0)
	v_cvt_pk_bf16_f32 v216, v140, v144
	v_cvt_pk_bf16_f32 v217, v148, v152
	v_cvt_pk_bf16_f32 v218, v160, v164
	v_cvt_pk_bf16_f32 v219, v172, v176
	v_cvt_pk_bf16_f32 v228, v141, v145
	v_cvt_pk_bf16_f32 v229, v149, v153
	v_cvt_pk_bf16_f32 v230, v161, v165
	v_cvt_pk_bf16_f32 v231, v173, v177
	v_cvt_pk_bf16_f32 v232, v142, v146
	v_cvt_pk_bf16_f32 v233, v150, v154
	v_cvt_pk_bf16_f32 v234, v162, v166
	v_cvt_pk_bf16_f32 v235, v174, v178
	ds_write_b128 v128, v[216:219] offset:9216
	ds_write_b128 v128, v[228:231] offset:10240
	ds_write_b128 v128, v[232:235] offset:11264
	s_waitcnt lgkmcnt(0)
	s_cmp_lg_u32 s3, 0
	s_cbranch_scc1 .Lp0a2_odd_sync
	v_mov_b32_e32 v132, 0x3f00
	s_mov_b32 s73, 0

.LBB0_82:
	v_readlane_b32 s3, v255, 5
	v_readlane_b32 s0, v255, 0
	v_readlane_b32 s1, v255, 1
	s_sub_u32 s0, s0, 0xc8
	s_subb_u32 s1, s1, 0
	s_load_dwordx2 s[74:75], s[0:1], 0x38
	v_lshrrev_b32_e32 v82, 4, v170
	s_lshl_b32 s73, s3, 7
	v_lshl_add_u32 v80, v82, 3, s73
	v_lshlrev_b32_e32 v83, 4, v170
	s_mul_i32 s73, s3, 0x3000
	v_add_u32_e32 v128, s73, v83
	v_mov_b32_e32 v129, v83
	v_add_u32_e32 v130, 0xc000, v83
	v_and_b32_e32 v134, 15, v170
	v_mul_u32_u24_e32 v134, 12, v134
	v_mov_b32_e32 v4, 0
	v_mov_b32_e32 v16, 0
	v_mov_b32_e32 v5, 0
	v_mov_b32_e32 v17, 0
	v_mov_b32_e32 v6, 0
	v_mov_b32_e32 v18, 0
	v_mov_b32_e32 v7, 0
	v_mov_b32_e32 v19, 0
	v_mov_b32_e32 v8, 0
	v_mov_b32_e32 v20, 0
	v_mov_b32_e32 v9, 0
	v_mov_b32_e32 v21, 0
	v_mov_b32_e32 v10, 0
	v_mov_b32_e32 v22, 0
	v_mov_b32_e32 v11, 0
	v_mov_b32_e32 v23, 0
	v_mov_b32_e32 v12, 0
	v_mov_b32_e32 v24, 0
	v_mov_b32_e32 v13, 0
	v_mov_b32_e32 v25, 0
	v_mov_b32_e32 v14, 0
	v_mov_b32_e32 v26, 0
	v_mov_b32_e32 v15, 0
	v_mov_b32_e32 v27, 0
	s_waitcnt lgkmcnt(0)
	s_mul_i32 s73, s91, 0xc0
	v_add_u32_e32 v82, s73, v134
	global_load_dwordx3 v[236:238], v82, s[74:75]
	s_waitcnt vmcnt(0)
	v_add_u32_e32 v82, 0, v80
	v_mad_u64_u32 v[2:3], s[0:1], v82, s69, v[226:227]
	global_load_dwordx3 v[28:30], v[2:3], off nt
	v_add_u32_e32 v82, 1, v80
	v_mad_u64_u32 v[2:3], s[0:1], v82, s69, v[226:227]
	global_load_dwordx3 v[32:34], v[2:3], off nt
	v_add_u32_e32 v82, 2, v80
	v_mad_u64_u32 v[2:3], s[0:1], v82, s69, v[226:227]
	global_load_dwordx3 v[36:38], v[2:3], off nt
	v_add_u32_e32 v82, 3, v80
	v_mad_u64_u32 v[2:3], s[0:1], v82, s69, v[226:227]
	global_load_dwordx3 v[40:42], v[2:3], off nt
	v_add_u32_e32 v82, 4, v80
	v_mad_u64_u32 v[2:3], s[0:1], v82, s69, v[226:227]
	global_load_dwordx3 v[44:46], v[2:3], off nt
	v_add_u32_e32 v82, 5, v80
	v_mad_u64_u32 v[2:3], s[0:1], v82, s69, v[226:227]
	global_load_dwordx3 v[48:50], v[2:3], off nt
	v_add_u32_e32 v82, 6, v80
	v_mad_u64_u32 v[2:3], s[0:1], v82, s69, v[226:227]
	global_load_dwordx3 v[52:54], v[2:3], off nt
	v_add_u32_e32 v82, 7, v80
	v_mad_u64_u32 v[2:3], s[0:1], v82, s69, v[226:227]
	global_load_dwordx3 v[56:58], v[2:3], off nt
	v_add_u32_e32 v82, 32, v80
	v_mad_u64_u32 v[2:3], s[0:1], v82, s69, v[226:227]
	global_load_dwordx3 v[60:62], v[2:3], off nt
	v_add_u32_e32 v82, 33, v80
	v_mad_u64_u32 v[2:3], s[0:1], v82, s69, v[226:227]
	global_load_dwordx3 v[64:66], v[2:3], off nt
	v_add_u32_e32 v82, 34, v80
	v_mad_u64_u32 v[2:3], s[0:1], v82, s69, v[226:227]
	global_load_dwordx3 v[68:70], v[2:3], off nt
	v_add_u32_e32 v82, 35, v80
	v_mad_u64_u32 v[2:3], s[0:1], v82, s69, v[226:227]
	global_load_dwordx3 v[72:74], v[2:3], off nt
	v_add_u32_e32 v82, 36, v80
	v_mad_u64_u32 v[2:3], s[0:1], v82, s69, v[226:227]
	global_load_dwordx3 v[76:78], v[2:3], off nt
	v_add_u32_e32 v82, 37, v80
	v_mad_u64_u32 v[2:3], s[0:1], v82, s69, v[226:227]
	global_load_dwordx3 v[84:86], v[2:3], off nt
	v_add_u32_e32 v82, 38, v80
	v_mad_u64_u32 v[2:3], s[0:1], v82, s69, v[226:227]
	global_load_dwordx3 v[88:90], v[2:3], off nt
	v_add_u32_e32 v82, 39, v80
	v_mad_u64_u32 v[2:3], s[0:1], v82, s69, v[226:227]
	global_load_dwordx3 v[92:94], v[2:3], off nt
	v_add_u32_e32 v82, 64, v80
	v_mad_u64_u32 v[2:3], s[0:1], v82, s69, v[226:227]
	global_load_dwordx3 v[96:98], v[2:3], off nt
	v_add_u32_e32 v82, 65, v80
	v_mad_u64_u32 v[2:3], s[0:1], v82, s69, v[226:227]
	global_load_dwordx3 v[100:102], v[2:3], off nt
	v_add_u32_e32 v82, 66, v80
	v_mad_u64_u32 v[2:3], s[0:1], v82, s69, v[226:227]
	global_load_dwordx3 v[104:106], v[2:3], off nt
	v_add_u32_e32 v82, 67, v80
	v_mad_u64_u32 v[2:3], s[0:1], v82, s69, v[226:227]
	global_load_dwordx3 v[108:110], v[2:3], off nt
	v_add_u32_e32 v82, 68, v80
	v_mad_u64_u32 v[2:3], s[0:1], v82, s69, v[226:227]
	global_load_dwordx3 v[112:114], v[2:3], off nt
	v_add_u32_e32 v82, 69, v80
	v_mad_u64_u32 v[2:3], s[0:1], v82, s69, v[226:227]
	global_load_dwordx3 v[116:118], v[2:3], off nt
	v_add_u32_e32 v82, 70, v80
	v_mad_u64_u32 v[2:3], s[0:1], v82, s69, v[226:227]
	global_load_dwordx3 v[120:122], v[2:3], off nt
	v_add_u32_e32 v82, 71, v80
	v_mad_u64_u32 v[2:3], s[0:1], v82, s69, v[226:227]
	global_load_dwordx3 v[124:126], v[2:3], off nt
	v_add_u32_e32 v82, 96, v80
	v_mad_u64_u32 v[2:3], s[0:1], v82, s69, v[226:227]
	global_load_dwordx3 v[140:142], v[2:3], off nt
	v_add_u32_e32 v82, 97, v80
	v_mad_u64_u32 v[2:3], s[0:1], v82, s69, v[226:227]
	global_load_dwordx3 v[144:146], v[2:3], off nt
	v_add_u32_e32 v82, 98, v80
	v_mad_u64_u32 v[2:3], s[0:1], v82, s69, v[226:227]
	global_load_dwordx3 v[148:150], v[2:3], off nt
	v_add_u32_e32 v82, 99, v80
	v_mad_u64_u32 v[2:3], s[0:1], v82, s69, v[226:227]
	global_load_dwordx3 v[152:154], v[2:3], off nt
	v_add_u32_e32 v82, 100, v80
	v_mad_u64_u32 v[2:3], s[0:1], v82, s69, v[226:227]
	global_load_dwordx3 v[160:162], v[2:3], off nt
	v_add_u32_e32 v82, 101, v80
	v_mad_u64_u32 v[2:3], s[0:1], v82, s69, v[226:227]
	global_load_dwordx3 v[164:166], v[2:3], off nt
	v_add_u32_e32 v82, 102, v80
	v_mad_u64_u32 v[2:3], s[0:1], v82, s69, v[226:227]
	global_load_dwordx3 v[172:174], v[2:3], off nt
	v_add_u32_e32 v82, 103, v80
	v_mad_u64_u32 v[2:3], s[0:1], v82, s69, v[226:227]
	global_load_dwordx3 v[176:178], v[2:3], off nt
	s_cmp_lg_u32 s3, 0
	s_cbranch_scc1 .Lnx_even_skip
	s_mov_b64 exec, 1
	v_mov_b32_e32 v196, 0x400
	s_mov_b32 s73, 0
